# prep_qk row loop software-pipelined: next row's six loads issued into spare registers before the current row is processed
# baseline (speedup 1.0000x reference)
.LBB0_338:
	s_mov_b64 s[12:13], s[84:85]
	v_mov_b32_e32 v0, v173
	s_getreg_b32 s1, hwreg(HW_REG_HW_ID, 0, 7)
	s_and_b32 s1, s1, 63
	s_lshl_b32 s1, s1, 2
	v_mov_b32_e32 v1, s1
	ds_read_b32 v1, v1
	v_readlane_b32 s6, v254, 10
	v_readlane_b32 s7, v254, 11
	s_andn2_b64 vcc, exec, s[6:7]
	s_waitcnt lgkmcnt(0)
	v_readfirstlane_b32 s1, v1
	s_lshl_b32 s1, s1, 6
	s_and_b32 s1, s1, 0x3fc0
	v_cndmask_b32_e64 v2, 0, 1, s[6:7]
	v_add_u32_e32 v1, s1, v0
	v_cmp_ne_u32_e64 s[10:11], 1, v2
	v_readfirstlane_b32 s1, v1
	s_cbranch_vccnz .LBB0_342
	s_ashr_i32 s1, s1, 6
	v_readlane_b32 s6, v254, 12
	s_add_i32 s14, s6, s1
	s_cmpk_gt_i32 s14, 0x3fff
	s_cbranch_scc1 .LBB0_342
	s_load_dwordx4 s[16:19], s[12:13], 0x80
	v_and_b32_e32 v1, 63, v0
	v_cmp_lt_u32_e32 vcc, 31, v1
	s_lshl_b32 s40, s70, 6
	s_ashr_i32 s15, s14, 31
	s_waitcnt lgkmcnt(0)
	v_mov_b32_e32 v1, s17
	v_mov_b32_e32 v2, s19
	v_cndmask_b32_e32 v3, v1, v2, vcc
	v_mov_b32_e32 v1, s16
	v_mov_b32_e32 v2, s18
	v_cndmask_b32_e32 v2, v1, v2, vcc
	v_mov_b32_e32 v1, 0x3e38aa3b
	v_cndmask_b32_e64 v14, v1, 1.0, vcc
	v_lshlrev_b32_e32 v1, 5, v0
	v_lshl_add_u64 v[2:3], s[40:41], 2, v[2:3]
	v_and_b32_e32 v160, 0x60, v1
	v_lshl_add_u64 v[16:17], v[2:3], 0, v[160:161]
	global_load_dwordx4 v[2:5], v[16:17], off offset:16
	global_load_dwordx4 v[6:9], v[16:17], off
	global_load_dwordx4 v[10:13], v[16:17], off offset:144
	global_load_dwordx4 v[20:23], v[16:17], off offset:128
	s_load_dwordx2 s[16:17], s[12:13], 0xe0
	s_lshl_b64 s[6:7], s[14:15], 8
	v_and_b32_e32 v0, 3, v0
	v_and_b32_e32 v160, 0x780, v1
	s_waitcnt vmcnt(16)
	v_lshl_or_b32 v32, v0, 6, s6
	v_mov_b32_e32 v33, s7
	v_mad_i64_i32 v[34:35], s[6:7], s14, v194, v[160:161]
	v_lshl_or_b32 v34, v0, 4, v34
	s_waitcnt vmcnt(3)
	v_pk_mul_f32 v[24:25], v[14:15], v[2:3] op_sel_hi:[0,1]
	s_waitcnt vmcnt(2)
	v_pk_mul_f32 v[16:17], v[14:15], v[6:7] op_sel_hi:[0,1]
	s_waitcnt vmcnt(1)
	v_pk_mul_f32 v[26:27], v[14:15], v[10:11] op_sel_hi:[0,1]
	s_waitcnt vmcnt(0)
	v_pk_mul_f32 v[18:19], v[14:15], v[20:21] op_sel_hi:[0,1]
	v_pk_mul_f32 v[20:21], v[14:15], v[8:9] op_sel_hi:[0,1]
	v_pk_mul_f32 v[22:23], v[14:15], v[22:23] op_sel_hi:[0,1]
	v_pk_mul_f32 v[28:29], v[14:15], v[4:5] op_sel_hi:[0,1]
	v_pk_mul_f32 v[30:31], v[14:15], v[12:13] op_sel_hi:[0,1]
	s_waitcnt lgkmcnt(0)
	v_lshl_add_u64 v[102:103], s[16:17], 0, v[34:35]
	v_add_co_u32_e32 v100, vcc, 0xc000000, v102
	s_mov_b64 s[6:7], 0xf600000
	s_nop 0
	v_addc_co_u32_e32 v101, vcc, 0, v103, vcc
	global_load_dwordx4 v[108:111], v[100:101], off
	global_load_dwordx4 v[112:115], v[100:101], off offset:64
	v_lshl_add_u64 v[102:103], s[16:17], 0, v[32:33]
	s_mov_b32 s1, 0xf600000
	v_lshl_add_u64 v[104:105], v[102:103], 0, s[6:7]
	v_add_co_u32_e32 v102, vcc, s1, v102
	s_add_i32 s14, s14, s38
	s_nop 0
	v_addc_co_u32_e32 v103, vcc, 0, v103, vcc
	global_load_dwordx4 v[116:119], v[102:103], off
	s_nop 0
	global_load_dwordx4 v[120:123], v[104:105], off offset:48
	global_load_dwordx4 v[124:127], v[104:105], off offset:32
	s_nop 0
	global_load_dwordx4 v[128:131], v[104:105], off offset:16
	v_lshl_add_u64 v[32:33], v[32:33], 0, s[66:67]
	v_lshl_add_u64 v[34:35], v[34:35], 0, s[62:63]
	s_cmpk_lt_i32 s14, 0x4000
	s_waitcnt vmcnt(0)
.LBB0_341:
	s_cmpk_lt_i32 s14, 0x4000
	s_cselect_b32 s15, 1, 0
	s_waitcnt vmcnt(2)
	v_mov_b32_e32 v46, v108
	v_mov_b32_e32 v47, v109
	v_mov_b32_e32 v48, v110
	v_mov_b32_e32 v49, v111
	v_mov_b32_e32 v50, v112
	v_mov_b32_e32 v51, v113
	v_mov_b32_e32 v52, v114
	v_mov_b32_e32 v53, v115
	v_mov_b32_e32 v12, v116
	v_mov_b32_e32 v13, v117
	v_mov_b32_e32 v14, v118
	v_mov_b32_e32 v15, v119
	v_mov_b32_e32 v0, v120
	v_mov_b32_e32 v1, v121
	v_mov_b32_e32 v2, v122
	v_mov_b32_e32 v3, v123
	v_mov_b32_e32 v4, v124
	v_mov_b32_e32 v5, v125
	v_mov_b32_e32 v6, v126
	v_mov_b32_e32 v7, v127
	v_mov_b32_e32 v8, v128
	v_mov_b32_e32 v9, v129
	v_mov_b32_e32 v10, v130
	v_mov_b32_e32 v11, v131
	v_mov_b32_e32 v36, v100
	v_mov_b32_e32 v37, v101
	v_lshl_add_u64 v[102:103], s[16:17], 0, v[34:35]
	v_add_co_u32_e32 v100, vcc, 0xc000000, v102
	s_mov_b64 s[6:7], 0xf600000
	s_nop 0
	v_addc_co_u32_e32 v101, vcc, 0, v103, vcc
	global_load_dwordx4 v[108:111], v[100:101], off
	global_load_dwordx4 v[112:115], v[100:101], off offset:64
	v_lshl_add_u64 v[102:103], s[16:17], 0, v[32:33]
	s_mov_b32 s1, 0xf600000
	v_lshl_add_u64 v[104:105], v[102:103], 0, s[6:7]
	v_add_co_u32_e32 v102, vcc, s1, v102
	s_add_i32 s14, s14, s38
	s_nop 0
	v_addc_co_u32_e32 v103, vcc, 0, v103, vcc
	global_load_dwordx4 v[116:119], v[102:103], off
	s_nop 0
	global_load_dwordx4 v[120:123], v[104:105], off offset:48
	global_load_dwordx4 v[124:127], v[104:105], off offset:32
	s_nop 0
	global_load_dwordx4 v[128:131], v[104:105], off offset:16
	v_lshl_add_u64 v[32:33], v[32:33], 0, s[66:67]
	v_lshl_add_u64 v[34:35], v[34:35], 0, s[62:63]
	s_cmpk_lt_i32 s14, 0x4000
	v_lshlrev_b32_e32 v40, 16, v49
	v_lshlrev_b32_e32 v38, 16, v53
	v_and_b32_e32 v39, 0xffff0000, v53
	v_and_b32_e32 v41, 0xffff0000, v49
	v_pk_mul_f32 v[42:43], v[38:39], v[38:39]
	v_and_b32_e32 v53, 0xffff0000, v47
	v_pk_fma_f32 v[54:55], v[40:41], v[40:41], v[42:43]
	v_lshlrev_b32_e32 v42, 16, v52
	v_and_b32_e32 v43, 0xffff0000, v52
	v_lshlrev_b32_e32 v52, 16, v47
	v_lshlrev_b32_e32 v60, 16, v46
	v_and_b32_e32 v61, 0xffff0000, v46
	v_lshlrev_b32_e32 v46, 16, v50
	v_and_b32_e32 v47, 0xffff0000, v50
	v_lshlrev_b32_e32 v56, 16, v51
	v_and_b32_e32 v57, 0xffff0000, v51
	v_pk_mul_f32 v[50:51], v[46:47], v[46:47]
	v_pk_mul_f32 v[58:59], v[56:57], v[56:57]
	v_pk_fma_f32 v[50:51], v[60:61], v[60:61], v[50:51]
	v_pk_fma_f32 v[58:59], v[52:53], v[52:53], v[58:59]
	v_add_f32_e32 v50, v50, v51
	v_lshlrev_b32_e32 v44, 16, v48
	v_and_b32_e32 v45, 0xffff0000, v48
	v_pk_mul_f32 v[48:49], v[42:43], v[42:43]
	v_add_f32_e32 v50, v58, v50
	v_pk_fma_f32 v[48:49], v[44:45], v[44:45], v[48:49]
	v_add_f32_e32 v50, v59, v50
	v_add_f32_e32 v48, v48, v50
	v_add_f32_e32 v48, v49, v48
	v_add_f32_e32 v48, v54, v48
	v_add_f32_e32 v48, v55, v48
	s_nop 1
	v_add_f32_dpp v48, v48, v48 quad_perm:[1,0,3,2] row_mask:0xf bank_mask:0xf bound_ctrl:1
	s_nop 1
	v_add_f32_dpp v48, v48, v48 quad_perm:[2,3,0,1] row_mask:0xf bank_mask:0xf bound_ctrl:1
	v_fmamk_f32 v48, v48, 0x3c800000, v182
	v_cmp_gt_f32_e32 vcc, s50, v48
	v_mul_f32_e32 v49, 0x4f800000, v48
	s_nop 0
	v_cndmask_b32_e32 v48, v48, v49, vcc
	v_sqrt_f32_e32 v49, v48
	s_nop 0
	v_add_u32_e32 v50, -1, v49
	v_fma_f32 v51, -v50, v49, v48
	v_cmp_ge_f32_e64 s[12:13], 0, v51
	v_add_u32_e32 v51, 1, v49
	s_nop 0
	v_cndmask_b32_e64 v50, v49, v50, s[12:13]
	v_fma_f32 v49, -v51, v49, v48
	v_cmp_lt_f32_e64 s[12:13], 0, v49
	s_nop 1
	v_cndmask_b32_e64 v49, v50, v51, s[12:13]
	v_mul_f32_e32 v50, 0x37800000, v49
	v_cndmask_b32_e32 v49, v49, v50, vcc
	v_cmp_class_f32_e32 vcc, v48, v183
	s_nop 1
	v_cndmask_b32_e32 v48, v49, v48, vcc
	v_div_scale_f32 v49, s[6:7], v48, v48, 1.0
	v_rcp_f32_e32 v50, v49
	s_nop 0
	v_fma_f32 v51, -v49, v50, 1.0
	v_fmac_f32_e32 v50, v51, v50
	v_div_scale_f32 v51, vcc, 1.0, v48, 1.0
	v_mul_f32_e32 v54, v51, v50
	v_fma_f32 v55, -v49, v54, v51
	v_fmac_f32_e32 v54, v55, v50
	v_fma_f32 v49, -v49, v54, v51
	v_div_fmas_f32 v49, v49, v50, v54
	v_div_fixup_f32 v50, v49, v48, 1.0
	v_pk_mul_f32 v[46:47], v[50:51], v[46:47] op_sel_hi:[0,1]
	v_pk_mul_f32 v[48:49], v[50:51], v[60:61] op_sel_hi:[0,1]
	v_pk_mul_f32 v[46:47], v[18:19], v[46:47]
	v_mov_b32_e32 v54, v12
	v_mov_b32_e32 v55, v14
	v_mov_b32_e32 v14, v13
	v_pk_mul_f32 v[48:49], v[16:17], v[48:49]
	v_pk_mul_f32 v[12:13], v[14:15], v[46:47]
	v_pk_mul_f32 v[46:47], v[54:55], v[46:47]
	v_pk_fma_f32 v[12:13], v[54:55], v[48:49], v[12:13] neg_lo:[0,0,1] neg_hi:[0,0,1]
	v_pk_fma_f32 v[14:15], v[14:15], v[48:49], v[46:47]
	v_pk_mul_f32 v[48:49], v[50:51], v[56:57] op_sel_hi:[0,1]
	v_cvt_pk_bf16_f32 v46, v14, v15
	v_pk_mul_f32 v[14:15], v[50:51], v[52:53] op_sel_hi:[0,1]
	v_pk_mul_f32 v[48:49], v[22:23], v[48:49]
	v_mov_b32_e32 v53, v10
	v_mov_b32_e32 v10, v9
	v_pk_mul_f32 v[14:15], v[20:21], v[14:15]
	v_mov_b32_e32 v52, v8
	v_pk_mul_f32 v[8:9], v[10:11], v[48:49]
	v_cvt_pk_bf16_f32 v12, v12, v13
	v_pk_fma_f32 v[8:9], v[52:53], v[14:15], v[8:9] neg_lo:[0,0,1] neg_hi:[0,0,1]
	s_nop 0
	v_cvt_pk_bf16_f32 v13, v8, v9
	v_pk_mul_f32 v[8:9], v[52:53], v[48:49]
	s_nop 0
	v_pk_fma_f32 v[8:9], v[10:11], v[14:15], v[8:9]
	v_pk_mul_f32 v[10:11], v[50:51], v[42:43] op_sel_hi:[0,1]
	v_cvt_pk_bf16_f32 v47, v8, v9
	v_pk_mul_f32 v[8:9], v[50:51], v[44:45] op_sel_hi:[0,1]
	v_pk_mul_f32 v[10:11], v[26:27], v[10:11]
	v_mov_b32_e32 v43, v6
	v_mov_b32_e32 v6, v5
	v_pk_mul_f32 v[8:9], v[24:25], v[8:9]
	v_mov_b32_e32 v42, v4
	v_pk_mul_f32 v[4:5], v[6:7], v[10:11]
	s_nop 0
	v_pk_fma_f32 v[4:5], v[42:43], v[8:9], v[4:5] neg_lo:[0,0,1] neg_hi:[0,0,1]
	s_nop 0
	v_cvt_pk_bf16_f32 v14, v4, v5
	v_pk_mul_f32 v[4:5], v[42:43], v[10:11]
	s_nop 0
	v_pk_fma_f32 v[4:5], v[6:7], v[8:9], v[4:5]
	v_pk_mul_f32 v[6:7], v[50:51], v[38:39] op_sel_hi:[0,1]
	v_cvt_pk_bf16_f32 v48, v4, v5
	v_pk_mul_f32 v[4:5], v[50:51], v[40:41] op_sel_hi:[0,1]
	v_pk_mul_f32 v[6:7], v[30:31], v[6:7]
	v_mov_b32_e32 v9, v2
	v_mov_b32_e32 v2, v1
	v_pk_mul_f32 v[4:5], v[28:29], v[4:5]
	v_mov_b32_e32 v8, v0
	v_pk_mul_f32 v[0:1], v[2:3], v[6:7]
	s_nop 0
	v_pk_fma_f32 v[0:1], v[8:9], v[4:5], v[0:1] neg_lo:[0,0,1] neg_hi:[0,0,1]
	s_nop 0
	v_cvt_pk_bf16_f32 v15, v0, v1
	v_pk_mul_f32 v[0:1], v[8:9], v[6:7]
	s_nop 0
	v_pk_fma_f32 v[0:1], v[2:3], v[4:5], v[0:1]
	s_nop 0
	v_cvt_pk_bf16_f32 v49, v0, v1
	global_store_dwordx4 v[36:37], v[12:15], off
	global_store_dwordx4 v[36:37], v[46:49], off offset:64
	s_cmp_lg_u32 s15, 0
	s_cbranch_scc1 .LBB0_341
	s_waitcnt vmcnt(0)
